# v132 plus the first row's row-sum partial loads of the beta/alpha GEMV issued at the top of the loop trip
# baseline (speedup 1.0000x reference)
; __device__ __forceinline__ float bf2f(bfu h) { return __uint_as_float(((unsigned)h) << 16); }
; #define SHX(v, m) shx_((v), (m), lane)
; __device__ void ba_item(const Params& p, int L, int rp) {
;     ...
;   for (int bt = 0; bt < 8; ++bt) {
;     bf16x8 h0[2], h1[2]; f32x4 ps[2][4];
;     _Pragma("unroll") for (int u = 0; u < 2; ++u) {
;       const int row = rp * 128 + wid * 16 + bt * 2 + u;
;       const bfu* hr = hb + (long)row * 1024 + lane * 16;
;       h0[u] = *(const bf16x8*)hr; h1[u] = *(const bf16x8*)(hr + 8);
;       _Pragma("unroll") for (int i = 0; i < 4; ++i) ps[u][i] = *(const f32x4*)(rowss + (long)row * 16 + i * 4);
;     }
;     _Pragma("unroll") for (int u = 0; u < 2; ++u) {
;       const int row = rp * 128 + wid * 16 + bt * 2 + u;
;       float hf[16];
;       _Pragma("unroll") for (int e = 0; e < 8; ++e) { hf[e] = bf2f((bfu)h0[u][e]); hf[8 + e] = bf2f((bfu)h1[u][e]); }
;       float a[8];
;       _Pragma("unroll") for (int j = 0; j < 8; ++j) {
;         float s = 0.f;
;         _Pragma("unroll") for (int e4 = 0; e4 < 4; ++e4) _Pragma("unroll") for (int e = 0; e < 4; ++e) s += hf[e4 * 4 + e] * wr_[j][e4][e];
;         _Pragma("unroll") for (int o = 32; o >= 1; o >>= 1) s += SHX(s, o);
;         a[j] = s;
;       }
.LBB0_616:
	s_waitcnt vmcnt(3)
	v_add_u32_e32 v132, s22, v0
	v_add_u32_e32 v164, 0xfffc8010, v132
	s_waitcnt lgkmcnt(3)
	v_ashrrev_i32_e32 v165, 31, v164
	v_lshlrev_b64 v[130:131], 11, v[164:165]
	v_lshl_add_u64 v[130:131], v[154:155], 0, v[130:131]
	s_waitcnt lgkmcnt(1)
	global_load_dwordx4 v[172:175], v[130:131], off
	s_waitcnt lgkmcnt(0)
	global_load_dwordx4 v[176:179], v[130:131], off offset:16
	v_add_u32_e32 v162, 0xfffc8011, v132
	v_ashrrev_i32_e32 v163, 31, v162
	v_lshlrev_b64 v[130:131], 11, v[162:163]
	v_lshlrev_b64 v[132:133], 6, v[162:163]
	v_lshl_add_u64 v[130:131], v[154:155], 0, v[130:131]
	s_waitcnt vmcnt(2)
	v_lshl_add_u64 v[142:143], s[24:25], 0, v[132:133]
	global_load_dwordx4 v[146:149], v[130:131], off
	global_load_dwordx4 v[150:153], v[130:131], off offset:16
	s_nop 0
	global_load_dwordx4 v[130:133], v[142:143], off offset:48
	global_load_dwordx4 v[134:137], v[142:143], off offset:32
	global_load_dwordx4 v[138:141], v[142:143], off offset:16
	s_nop 0
	global_load_dwordx4 v[228:231], v[142:143], off offset:-16
	global_load_dwordx4 v[232:235], v[142:143], off offset:-32
	global_load_dwordx4 v[236:239], v[142:143], off offset:-48
	global_load_dwordx4 v[240:243], v[142:143], off offset:-64
	global_load_dwordx4 v[142:145], v[142:143], off
	s_waitcnt vmcnt(11)
	v_lshlrev_b32_e32 v182, 16, v172
	v_and_b32_e32 v184, 0xffff0000, v172
	s_waitcnt vmcnt(10)
	v_lshlrev_b32_e32 v187, 16, v177
	v_and_b32_e32 v189, 0xffff0000, v177
	v_fma_f32 v177, v58, v182, 0
	v_lshlrev_b32_e32 v186, 16, v173
	v_fmac_f32_e32 v177, v59, v184
	v_and_b32_e32 v188, 0xffff0000, v173
	v_fmac_f32_e32 v177, v60, v186
	v_lshlrev_b32_e32 v190, 16, v174
	v_fmac_f32_e32 v177, v61, v188
	v_and_b32_e32 v192, 0xffff0000, v174
	v_fmac_f32_e32 v177, v50, v190
	v_lshlrev_b32_e32 v194, 16, v175
	v_fmac_f32_e32 v177, v51, v192
	v_lshlrev_b32_e32 v191, 16, v178
	v_and_b32_e32 v193, 0xffff0000, v178
	v_and_b32_e32 v196, 0xffff0000, v175
	v_fma_f32 v178, v62, v182, 0
	v_fmac_f32_e32 v177, v52, v194
	v_lshlrev_b32_e32 v183, 16, v176
	v_fmac_f32_e32 v178, v63, v184
	v_fmac_f32_e32 v177, v53, v196
	v_and_b32_e32 v185, 0xffff0000, v176
	v_fmac_f32_e32 v178, v64, v186
	v_fmac_f32_e32 v177, v54, v183
	v_fmac_f32_e32 v178, v65, v188
	v_fmac_f32_e32 v177, v55, v185
	v_fmac_f32_e32 v178, v70, v190
	v_fmac_f32_e32 v177, v56, v187
	v_fmac_f32_e32 v178, v71, v192
	v_fmac_f32_e32 v177, v57, v189
	v_fmac_f32_e32 v178, v72, v194
	v_fmac_f32_e32 v177, v66, v191
	v_lshlrev_b32_e32 v195, 16, v179
	v_fmac_f32_e32 v178, v73, v196
	v_fmac_f32_e32 v177, v67, v193
	v_and_b32_e32 v197, 0xffff0000, v179
	v_fmac_f32_e32 v178, v74, v183
	v_fmac_f32_e32 v177, v68, v195
	v_fmac_f32_e32 v178, v75, v185
	v_fmac_f32_e32 v177, v69, v197
	ds_bpermute_b32 v180, v166, v177
	v_fmac_f32_e32 v178, v76, v187
	v_fmac_f32_e32 v178, v77, v189
	v_fmac_f32_e32 v178, v78, v191
	v_fmac_f32_e32 v178, v79, v193
	v_fmac_f32_e32 v178, v80, v195
	v_fmac_f32_e32 v178, v81, v197
	s_waitcnt lgkmcnt(0)
	v_add_f32_e32 v177, v177, v180
	ds_bpermute_b32 v181, v166, v178
	ds_bpermute_b32 v180, v167, v177
	v_fma_f32 v172, v2, v182, 0
	v_fma_f32 v173, v26, v182, 0
	v_fma_f32 v176, v30, v182, 0
	s_waitcnt lgkmcnt(1)
	v_add_f32_e32 v178, v178, v181
	s_waitcnt lgkmcnt(0)
	v_add_f32_e32 v177, v177, v180
	ds_bpermute_b32 v181, v167, v178
	ds_bpermute_b32 v180, v168, v177
	v_fma_f32 v200, v94, v182, 0
	v_fmac_f32_e32 v172, v3, v184
	v_fmac_f32_e32 v173, v27, v184
	s_waitcnt lgkmcnt(1)
	v_add_f32_e32 v178, v178, v181
	s_waitcnt lgkmcnt(0)
	v_add_f32_e32 v177, v177, v180
	ds_bpermute_b32 v181, v168, v178
	ds_bpermute_b32 v180, v169, v177
	v_fmac_f32_e32 v176, v31, v184
	v_fmac_f32_e32 v200, v95, v184
	v_fmac_f32_e32 v172, v4, v186
	s_waitcnt lgkmcnt(1)
	v_add_f32_e32 v178, v178, v181
	s_waitcnt lgkmcnt(0)
	v_add_f32_e32 v180, v177, v180
	ds_bpermute_b32 v181, v169, v178
	ds_bpermute_b32 v198, v170, v180
	v_fmac_f32_e32 v173, v28, v186
	v_fmac_f32_e32 v176, v32, v186
	v_fmac_f32_e32 v200, v96, v186
	s_waitcnt lgkmcnt(1)
	v_add_f32_e32 v181, v178, v181
	s_waitcnt lgkmcnt(0)
	v_add_f32_e32 v178, v180, v198
	v_fma_f32 v198, v90, v182, 0
	v_fma_f32 v182, v122, v182, 0
	v_fmac_f32_e32 v198, v91, v184
	v_fmac_f32_e32 v182, v123, v184
	v_fmac_f32_e32 v198, v92, v186
	v_fmac_f32_e32 v182, v124, v186
	v_fmac_f32_e32 v172, v5, v188
	v_fmac_f32_e32 v173, v29, v188
	v_fmac_f32_e32 v176, v33, v188
	v_fmac_f32_e32 v198, v93, v188
	v_fmac_f32_e32 v200, v97, v188
	v_fmac_f32_e32 v182, v125, v188
	v_fmac_f32_e32 v172, v6, v190
	v_fmac_f32_e32 v173, v18, v190
	v_fmac_f32_e32 v176, v38, v190
	v_fmac_f32_e32 v198, v82, v190
	v_fmac_f32_e32 v200, v102, v190
	v_fmac_f32_e32 v182, v114, v190
	v_fmac_f32_e32 v172, v7, v192
	v_fmac_f32_e32 v173, v19, v192
	v_fmac_f32_e32 v176, v39, v192
	v_fmac_f32_e32 v198, v83, v192
	v_fmac_f32_e32 v200, v103, v192
	v_fmac_f32_e32 v182, v115, v192
	v_fmac_f32_e32 v172, v8, v194
	v_fmac_f32_e32 v173, v20, v194
	v_fmac_f32_e32 v176, v40, v194
	v_fmac_f32_e32 v198, v84, v194
	v_fmac_f32_e32 v200, v104, v194
	v_fmac_f32_e32 v182, v116, v194
	v_fmac_f32_e32 v172, v9, v196
	v_fmac_f32_e32 v173, v21, v196
	v_fmac_f32_e32 v176, v41, v196
	v_fmac_f32_e32 v198, v85, v196
	v_fmac_f32_e32 v200, v105, v196
	v_fmac_f32_e32 v182, v117, v196
	v_fmac_f32_e32 v172, v10, v183
	v_fmac_f32_e32 v173, v22, v183
	v_fmac_f32_e32 v176, v42, v183
	v_fmac_f32_e32 v198, v86, v183
	v_fmac_f32_e32 v200, v106, v183
	v_fmac_f32_e32 v182, v118, v183
	v_fmac_f32_e32 v172, v11, v185
	v_fmac_f32_e32 v173, v23, v185
	v_fmac_f32_e32 v176, v43, v185
	v_fmac_f32_e32 v198, v87, v185
	v_fmac_f32_e32 v200, v107, v185
	v_fmac_f32_e32 v182, v119, v185
	v_fmac_f32_e32 v172, v12, v187
	v_fmac_f32_e32 v173, v24, v187
	v_fmac_f32_e32 v176, v44, v187
	v_fmac_f32_e32 v198, v88, v187
	v_fmac_f32_e32 v200, v108, v187
	v_fmac_f32_e32 v182, v120, v187
	v_fmac_f32_e32 v172, v13, v189
	v_fmac_f32_e32 v173, v25, v189
	v_fmac_f32_e32 v176, v45, v189
	ds_bpermute_b32 v199, v170, v181
	v_fmac_f32_e32 v198, v89, v189
	v_fmac_f32_e32 v200, v109, v189
	v_fmac_f32_e32 v182, v121, v189
	v_fmac_f32_e32 v172, v14, v191
	v_fmac_f32_e32 v173, v34, v191
	v_fmac_f32_e32 v176, v46, v191
	v_fmac_f32_e32 v198, v98, v191
	v_fmac_f32_e32 v200, v110, v191
	v_fmac_f32_e32 v182, v126, v191
	v_fmac_f32_e32 v172, v15, v193
	v_fmac_f32_e32 v173, v35, v193
	v_fmac_f32_e32 v176, v47, v193
	v_fmac_f32_e32 v198, v99, v193
	v_fmac_f32_e32 v200, v111, v193
	v_fmac_f32_e32 v182, v127, v193
	v_fmac_f32_e32 v172, v16, v195
	v_fmac_f32_e32 v173, v36, v195
	v_fmac_f32_e32 v176, v48, v195
	v_fmac_f32_e32 v198, v100, v195
	v_fmac_f32_e32 v200, v112, v195
	v_fmac_f32_e32 v182, v128, v195
	v_fmac_f32_e32 v172, v17, v197
	v_fmac_f32_e32 v173, v37, v197
	v_fmac_f32_e32 v176, v49, v197
	v_fmac_f32_e32 v198, v101, v197
	v_fmac_f32_e32 v200, v113, v197
	v_fmac_f32_e32 v182, v129, v197
	ds_bpermute_b32 v174, v166, v172
	ds_bpermute_b32 v175, v166, v173
	ds_bpermute_b32 v179, v166, v176
	s_waitcnt lgkmcnt(3)
; __device__ __forceinline__ float fexp(float x) { return __builtin_amdgcn_exp2f(x * 1.4426950408889634f); }
; __device__ __forceinline__ float flog(float x) { return __builtin_amdgcn_logf(x) * 0.6931471805599453f; }
; __device__ __forceinline__ float frsq(float x) { return __builtin_amdgcn_rsqf(x); }
; __device__ __forceinline__ float sigmoidf_(float x) { return frcp(1.0f + fexp(-x)); }
; __device__ void ba_item(const Params& p, int L, int rp) {
;     ...
;       if (lane < 8) {
;         float s16 = 0.f;
;         _Pragma("unroll") for (int i = 0; i < 4; ++i) s16 += (ps[u][i][0] + ps[u][i][1]) + (ps[u][i][2] + ps[u][i][3]);
;         float rs = frsq(s16 * (1.0f / 1024.0f) + 1e-6f);
;         float v = 0.f;
;         _Pragma("unroll") for (int j = 0; j < 8; ++j) if (lane == j) v = a[j];
;         v *= rs;
;         float r;
;         if (lane < 4) r = sigmoidf_(v);
;         else {
;           int hh = lane - 4;
;           float z = v + p.dn_dt_bias[(L >> 1) * 4 + hh];
;           float sp = (z > 20.f) ? z : flog(1.0f + fexp(z));
;           r = -fexp(p.dn_a_log[(L >> 1) * 4 + hh]) * sp;
;         }
;         miscw[MF_BG + (long)row * 8 + lane] = r;
	v_add_f32_e32 v180, v181, v199
	ds_bpermute_b32 v199, v166, v198
	ds_bpermute_b32 v202, v166, v200
	ds_bpermute_b32 v183, v166, v182
	s_waitcnt lgkmcnt(5)
	v_add_f32_e32 v172, v172, v174
	s_waitcnt lgkmcnt(4)
	v_add_f32_e32 v173, v173, v175
	s_waitcnt lgkmcnt(3)
	v_add_f32_e32 v176, v176, v179
	s_waitcnt lgkmcnt(2)
	v_add_f32_e32 v184, v198, v199
	s_waitcnt lgkmcnt(1)
	v_add_f32_e32 v186, v200, v202
	s_waitcnt lgkmcnt(0)
	v_add_f32_e32 v182, v182, v183
	ds_bpermute_b32 v174, v167, v172
	ds_bpermute_b32 v175, v167, v173
	ds_bpermute_b32 v179, v167, v176
	ds_bpermute_b32 v185, v167, v184
	ds_bpermute_b32 v187, v167, v186
	ds_bpermute_b32 v183, v167, v182
	s_waitcnt lgkmcnt(5)
	v_add_f32_e32 v172, v172, v174
	s_waitcnt lgkmcnt(4)
	v_add_f32_e32 v173, v173, v175
	s_waitcnt lgkmcnt(3)
	v_add_f32_e32 v176, v176, v179
	s_waitcnt lgkmcnt(2)
	v_add_f32_e32 v184, v184, v185
	s_waitcnt lgkmcnt(1)
	v_add_f32_e32 v186, v186, v187
	s_waitcnt lgkmcnt(0)
	v_add_f32_e32 v182, v182, v183
	ds_bpermute_b32 v174, v168, v172
	ds_bpermute_b32 v175, v168, v173
	ds_bpermute_b32 v179, v168, v176
	ds_bpermute_b32 v185, v168, v184
	ds_bpermute_b32 v187, v168, v186
	ds_bpermute_b32 v183, v168, v182
	s_waitcnt lgkmcnt(5)
	v_add_f32_e32 v172, v172, v174
	s_waitcnt lgkmcnt(4)
	v_add_f32_e32 v173, v173, v175
	s_waitcnt lgkmcnt(3)
	v_add_f32_e32 v176, v176, v179
	s_waitcnt lgkmcnt(2)
	v_add_f32_e32 v184, v184, v185
	s_waitcnt lgkmcnt(1)
	v_add_f32_e32 v186, v186, v187
	s_waitcnt lgkmcnt(0)
	v_add_f32_e32 v182, v182, v183
	ds_bpermute_b32 v174, v169, v172
	ds_bpermute_b32 v175, v169, v173
	ds_bpermute_b32 v179, v169, v176
	ds_bpermute_b32 v185, v169, v184
	ds_bpermute_b32 v187, v169, v186
	ds_bpermute_b32 v183, v169, v182
	s_waitcnt lgkmcnt(5)
	v_add_f32_e32 v172, v172, v174
	s_waitcnt lgkmcnt(4)
	v_add_f32_e32 v173, v173, v175
	s_waitcnt lgkmcnt(3)
	v_add_f32_e32 v176, v176, v179
	s_waitcnt lgkmcnt(2)
	v_add_f32_e32 v184, v184, v185
	s_waitcnt lgkmcnt(1)
	v_add_f32_e32 v186, v186, v187
	s_waitcnt lgkmcnt(0)
	v_add_f32_e32 v188, v182, v183
	ds_bpermute_b32 v174, v170, v172
	ds_bpermute_b32 v175, v170, v173
	ds_bpermute_b32 v179, v170, v176
	ds_bpermute_b32 v185, v170, v184
	ds_bpermute_b32 v187, v170, v186
	ds_bpermute_b32 v189, v170, v188
	s_waitcnt lgkmcnt(5)
	v_add_f32_e32 v172, v172, v174
	s_waitcnt lgkmcnt(4)
	v_add_f32_e32 v174, v173, v175
	s_waitcnt lgkmcnt(3)
	v_add_f32_e32 v176, v176, v179
	s_waitcnt lgkmcnt(2)
	v_add_f32_e32 v182, v184, v185
	s_waitcnt lgkmcnt(1)
	v_add_f32_e32 v184, v186, v187
	s_waitcnt lgkmcnt(0)
	v_add_f32_e32 v186, v188, v189
	ds_bpermute_b32 v173, v171, v172
	ds_bpermute_b32 v175, v171, v174
	ds_bpermute_b32 v177, v171, v176
	ds_bpermute_b32 v179, v171, v178
	ds_bpermute_b32 v181, v171, v180
	ds_bpermute_b32 v183, v171, v182
	ds_bpermute_b32 v185, v171, v184
	ds_bpermute_b32 v187, v171, v186
	s_and_saveexec_b64 s[12:13], vcc
	s_cbranch_execz .LBB0_622
	s_waitcnt lgkmcnt(7)
	v_add_f32_e32 v195, v172, v173
	v_lshlrev_b64 v[172:173], 6, v[164:165]
	s_waitcnt lgkmcnt(1)
	v_add_f32_e32 v189, v184, v185
	v_lshl_add_u64 v[184:185], s[24:25], 0, v[172:173]
	s_waitcnt lgkmcnt(0)
	v_add_f32_e32 v188, v186, v187
	v_add_f32_e32 v190, v182, v183
	v_add_f32_e32 v191, v180, v181
	v_add_f32_e32 v192, v178, v179
	v_add_f32_e32 v193, v176, v177
	v_add_f32_e32 v194, v174, v175
	s_waitcnt vmcnt(1)
	v_mov_b64_e32 v[172:173], v[228:229]
	v_mov_b64_e32 v[174:175], v[230:231]
	v_mov_b64_e32 v[176:177], v[232:233]
	v_mov_b64_e32 v[178:179], v[234:235]
	v_mov_b64_e32 v[180:181], v[236:237]
	v_mov_b64_e32 v[182:183], v[238:239]
	v_mov_b64_e32 v[184:185], v[240:241]
	v_mov_b64_e32 v[186:187], v[242:243]
	s_waitcnt vmcnt(3)
	v_add_f32_e32 v172, v172, v173
	s_waitcnt vmcnt(2)
	v_add_f32_e32 v176, v176, v177
	s_waitcnt vmcnt(1)
	v_add_f32_e32 v180, v180, v181
	s_waitcnt vmcnt(0)
	v_add_f32_e32 v184, v184, v185
	v_add_f32_e32 v185, v186, v187
	v_add_f32_e32 v184, v184, v185
	v_add_f32_e32 v181, v182, v183
	v_add_f32_e32 v184, 0, v184
	v_add_f32_e32 v180, v180, v181
	v_add_f32_e32 v177, v178, v179
	v_add_f32_e32 v173, v174, v175
	v_add_f32_e32 v180, v180, v184
	v_add_f32_e32 v176, v176, v177
	v_add_f32_e32 v172, v172, v173
	v_cndmask_b32_e64 v173, 0, v195, s[40:41]
	v_add_f32_e32 v176, v176, v180
	v_cndmask_b32_e64 v173, v173, v194, s[42:43]
	v_add_f32_e32 v172, v172, v176
	v_cndmask_b32_e64 v173, v173, v193, s[44:45]
	v_fmamk_f32 v172, v172, 0x3a800000, v201
	v_cndmask_b32_e64 v173, v173, v192, s[46:47]
	v_cndmask_b32_e64 v173, v173, v191, s[48:49]
	v_rsq_f32_e32 v172, v172
	v_cndmask_b32_e64 v173, v173, v190, s[50:51]
	v_cndmask_b32_e64 v173, v173, v189, s[52:53]
	v_cndmask_b32_e64 v173, v173, v188, s[54:55]
	v_mul_f32_e32 v173, v173, v172
	s_and_saveexec_b64 s[0:1], s[38:39]
	s_xor_b64 s[14:15], exec, s[0:1]
	s_cbranch_execz .LBB0_619
	v_mov_b32_e32 v172, v203
	s_waitcnt vmcnt(0)
	v_add_f32_e32 v172, v173, v172
	v_mul_f32_e32 v173, 0x3fb8aa3b, v172
	v_exp_f32_e32 v173, v173
	v_cmp_lt_f32_e64 s[0:1], s57, v172
	v_add_f32_e32 v173, 1.0, v173
	v_log_f32_e32 v173, v173
	s_nop 0
	v_mul_f32_e32 v173, 0x3f317218, v173
	v_cndmask_b32_e64 v172, v173, v172, s[0:1]
	v_mov_b32_e32 v173, v205
	s_waitcnt vmcnt(0)
	v_mul_f32_e32 v173, 0x3fb8aa3b, v173
	v_exp_f32_e32 v173, v173
	s_nop 0
	v_mul_f32_e64 v172, v172, -v173
